# speedup vs baseline: 1.0145x; 1.0048x over previous
.LBB0_187:
	s_or_b64 exec, exec, s[10:11]
	s_lshl_b32 s34, s18, 6
	s_lshl_b32 s3, s3, 24
	s_add_u32 s10, s37, s3
	s_addc_u32 s11, s91, 0
	s_add_u32 s3, s46, s3
	s_addc_u32 s18, s73, 0
	s_lshl_b32 s19, s34, 1
	s_add_u32 s40, s10, s19
	s_addc_u32 s41, s11, 0
	s_waitcnt vmcnt(0)
	v_cndmask_b32_e64 v1, 0, 1, s[8:9]
	s_add_u32 s42, s3, s19
	v_cmp_ne_u32_e32 vcc, 0, v1
	v_cndmask_b32_e64 v1, 0, 1, s[6:7]
	s_addc_u32 s43, s18, 0
	s_bcnt1_i32_b64 s3, vcc
	v_cmp_ne_u32_e32 vcc, 0, v1
	s_bcnt1_i32_b64 s6, vcc
	s_add_i32 s6, s6, s3
	s_and_b32 s3, s6, 0xfe
	s_add_i32 s10, s77, -4
	s_min_u32 s3, s3, s10
	v_ashrrev_i32_e32 v158, 3, v143
	s_lshl_b32 s78, s3, 6
	v_lshlrev_b32_e32 v33, 3, v143
	v_add_u32_e32 v2, s78, v158
	s_add_i32 s6, s78, 64
	v_and_b32_e32 v159, 56, v33
	v_ashrrev_i32_e32 v3, 31, v2
	v_add_u32_e32 v10, s6, v158
	v_lshlrev_b64 v[2:3], 11, v[2:3]
	v_lshlrev_b32_e32 v1, 1, v159
	v_ashrrev_i32_e32 v11, 31, v10
	v_or_b32_e32 v14, s6, v144
	v_or_b32_e32 v2, v2, v1
	v_lshlrev_b64 v[10:11], 11, v[10:11]
	v_ashrrev_i32_e32 v15, 31, v14
	v_lshl_add_u64 v[4:5], s[42:43], 0, v[2:3]
	v_lshl_add_u64 v[6:7], s[40:41], 0, v[2:3]
	v_or_b32_e32 v10, v10, v1
	v_lshl_add_u64 v[14:15], v[14:15], 2, s[38:39]
	global_load_dwordx4 v[2:5], v[4:5], off
	s_nop 0
	global_load_dwordx4 v[6:9], v[6:7], off
	v_lshl_add_u64 v[12:13], s[42:43], 0, v[10:11]
	v_lshl_add_u64 v[10:11], s[40:41], 0, v[10:11]
	global_load_dword v160, v[14:15], off
	global_load_dwordx4 v[112:115], v[12:13], off
	global_load_dwordx4 v[116:119], v[10:11], off
	v_lshlrev_b32_e32 v10, 8, v143
	v_lshlrev_b32_e32 v11, 6, v158
	v_lshlrev_b32_e32 v12, 4, v158
	v_and_b32_e32 v13, 8, v33
	s_mov_b32 s8, 0x7ffff800
	v_and_b32_e32 v10, 0x600, v10
	v_and_b32_e32 v15, 0x1f0, v12
	v_and_or_b32 v11, v11, s8, v13
	v_lshlrev_b32_e32 v14, 7, v158
	v_lshlrev_b32_e32 v12, 3, v158
	v_and_b32_e32 v12, 0x70, v12
	v_or3_b32 v10, v11, v15, v10
	v_cmp_gt_i32_e64 s[6:7], 64, v143
	v_bitop3_b32 v161, v1, v14, v12 bitop3:0xde
	v_lshlrev_b32_e32 v162, 1, v10
	v_cmp_lt_i32_e32 vcc, 63, v143
	s_waitcnt vmcnt(4)
	ds_write_b128 v162, v[2:5]
	s_waitcnt vmcnt(3)
	ds_write_b128 v161, v[6:9] offset:24576
	s_and_saveexec_b64 s[8:9], vcc
	s_xor_b64 s[8:9], exec, s[8:9]
	s_cbranch_execz .LBB0_189
	s_waitcnt vmcnt(1)
	ds_write_b128 v162, v[112:115] offset:8192
	s_waitcnt vmcnt(0)
	ds_write_b128 v161, v[116:119] offset:32768

.LBB0_191:
	s_or_b64 exec, exec, s[8:9]
	v_lshlrev_b32_e32 v1, 3, v143
	v_or_b32_e32 v152, v0, v148
	v_lshlrev_b32_e32 v0, 7, v148
	v_and_b32_e32 v1, 0x70, v1
	v_or_b32_e32 v2, 32, v128
	v_bitop3_b32 v155, v2, v0, v1 bitop3:0xde
	v_or_b32_e32 v2, 64, v128
	v_bitop3_b32 v154, v2, v0, v1 bitop3:0xde
	v_or_b32_e32 v2, 0x60, v128
	s_add_i32 s8, s78, 0x80
	v_bitop3_b32 v156, v128, v0, v1 bitop3:0xde
	v_bitop3_b32 v153, v2, v0, v1 bitop3:0xde
	v_add_u32_e32 v0, s8, v158
	v_ashrrev_i32_e32 v1, 31, v0
	v_lshlrev_b64 v[0:1], 11, v[0:1]
	v_lshl_or_b32 v0, v159, 1, v0
	v_lshl_add_u64 v[2:3], s[42:43], 0, v[0:1]
	v_lshl_add_u64 v[0:1], s[40:41], 0, v[0:1]
	s_waitcnt lgkmcnt(0)
	s_barrier
	global_load_dwordx4 v[120:123], v[2:3], off
	global_load_dwordx4 v[124:127], v[0:1], off
	v_or_b32_e32 v0, s8, v144
	v_ashrrev_i32_e32 v1, 31, v0
	v_lshl_add_u64 v[0:1], v[0:1], 2, s[38:39]
	global_load_dword v165, v[0:1], off
	ds_read_b128 v[4:7], v156 offset:24576
	ds_read_b128 v[16:19], v128 offset:51200
	ds_read_b128 v[20:23], v128 offset:51232
	ds_read_b128 v[24:27], v128 offset:51264
	ds_read_b128 v[28:31], v128 offset:51296
	ds_read_b128 v[34:37], v156 offset:28672
	ds_read_b128 v[0:3], v128 offset:51328
	s_sub_i32 s8, s3, s10
	v_lshlrev_b32_e32 v157, 2, v146
	s_waitcnt lgkmcnt(2)
	v_mfma_f32_32x32x16_bf16 v[16:31], v[4:7], v[96:99], v[16:31]
	ds_read_b128 v[4:7], v128 offset:51360
	ds_read_b128 v[8:11], v128 offset:51392
	ds_read_b128 v[12:15], v128 offset:51424
	s_cmp_lt_i32 s8, 0
	s_waitcnt lgkmcnt(0)
	v_mfma_f32_32x32x16_bf16 v[0:15], v[34:37], v[96:99], v[0:15]
	ds_read_b128 v[34:37], v155 offset:24576
	s_waitcnt lgkmcnt(0)
	v_mfma_f32_32x32x16_bf16 v[16:31], v[34:37], v[100:103], v[16:31]
	ds_read_b128 v[34:37], v155 offset:28672
	s_waitcnt lgkmcnt(0)
	v_mfma_f32_32x32x16_bf16 v[0:15], v[34:37], v[100:103], v[0:15]
	ds_read_b128 v[34:37], v154 offset:24576
	s_waitcnt lgkmcnt(0)
	v_mfma_f32_32x32x16_bf16 v[16:31], v[34:37], v[104:107], v[16:31]
	ds_read_b128 v[34:37], v154 offset:28672
	s_waitcnt lgkmcnt(0)
	v_mfma_f32_32x32x16_bf16 v[0:15], v[34:37], v[104:107], v[0:15]
	ds_read_b128 v[34:37], v153 offset:24576
	s_waitcnt lgkmcnt(0)
	v_mfma_f32_32x32x16_bf16 v[16:31], v[34:37], v[108:111], v[16:31]
	ds_read_b128 v[34:37], v153 offset:28672
	s_waitcnt lgkmcnt(0)
	v_mfma_f32_32x32x16_bf16 v[0:15], v[34:37], v[108:111], v[0:15]
	s_cbranch_scc1 .LBB0_193
	v_lshl_or_b32 v34, s8, 6, v157
	v_or_b32_e32 v35, 32, v34
	v_cmp_le_i32_e32 vcc, v35, v152
	v_or_b32_e32 v35, 33, v34
	s_nop 6
	v_cndmask_b32_e32 v0, v176, v0, vcc
	v_cmp_lt_i32_e32 vcc, v34, v152
	s_nop 1
	v_cndmask_b32_e32 v17, v176, v17, vcc
	v_cmp_le_i32_e32 vcc, v34, v152
	s_nop 1
	v_cndmask_b32_e32 v16, v176, v16, vcc
	v_cmp_le_i32_e32 vcc, v35, v152
	v_or_b32_e32 v35, 2, v34
	s_nop 0
	v_cndmask_b32_e32 v1, v176, v1, vcc
	v_cmp_le_i32_e32 vcc, v35, v152
	v_or_b32_e32 v35, 34, v34
	s_nop 0
	v_cndmask_b32_e32 v18, v176, v18, vcc
	v_cmp_le_i32_e32 vcc, v35, v152
	v_or_b32_e32 v35, 3, v34
	s_nop 0
	v_cndmask_b32_e32 v2, v176, v2, vcc
	v_cmp_le_i32_e32 vcc, v35, v152
	v_or_b32_e32 v35, 35, v34
	s_nop 0
	v_cndmask_b32_e32 v19, v176, v19, vcc
	v_cmp_le_i32_e32 vcc, v35, v152
	v_or_b32_e32 v35, 8, v34
	s_nop 0
	v_cndmask_b32_e32 v3, v176, v3, vcc
	v_cmp_le_i32_e32 vcc, v35, v152
	v_or_b32_e32 v35, 40, v34
	s_nop 0
	v_cndmask_b32_e32 v20, v176, v20, vcc
	v_cmp_le_i32_e32 vcc, v35, v152
	v_or_b32_e32 v35, 9, v34
	s_nop 0
	v_cndmask_b32_e32 v4, v176, v4, vcc
	v_cmp_le_i32_e32 vcc, v35, v152
	v_or_b32_e32 v35, 41, v34
	s_nop 0
	v_cndmask_b32_e32 v21, v176, v21, vcc
	v_cmp_le_i32_e32 vcc, v35, v152
	v_or_b32_e32 v35, 10, v34
	s_nop 0
	v_cndmask_b32_e32 v5, v176, v5, vcc
	v_cmp_le_i32_e32 vcc, v35, v152
	v_or_b32_e32 v35, 42, v34
	s_nop 0
	v_cndmask_b32_e32 v22, v176, v22, vcc
	v_cmp_le_i32_e32 vcc, v35, v152
	v_or_b32_e32 v35, 11, v34
	s_nop 0
	v_cndmask_b32_e32 v6, v176, v6, vcc
	v_cmp_le_i32_e32 vcc, v35, v152
	v_or_b32_e32 v35, 43, v34
	s_nop 0
	v_cndmask_b32_e32 v23, v176, v23, vcc
	v_cmp_le_i32_e32 vcc, v35, v152
	v_or_b32_e32 v35, 16, v34
	s_nop 0
	v_cndmask_b32_e32 v7, v176, v7, vcc
	v_cmp_le_i32_e32 vcc, v35, v152
	v_or_b32_e32 v35, 48, v34
	s_nop 0
	v_cndmask_b32_e32 v24, v176, v24, vcc
	v_cmp_le_i32_e32 vcc, v35, v152
	v_or_b32_e32 v35, 17, v34
	s_nop 0
	v_cndmask_b32_e32 v8, v176, v8, vcc
	v_cmp_le_i32_e32 vcc, v35, v152
	v_or_b32_e32 v35, 49, v34
	s_nop 0
	v_cndmask_b32_e32 v25, v176, v25, vcc
	v_cmp_le_i32_e32 vcc, v35, v152
	v_or_b32_e32 v35, 18, v34
	s_nop 0
	v_cndmask_b32_e32 v9, v176, v9, vcc
	v_cmp_le_i32_e32 vcc, v35, v152
	v_or_b32_e32 v35, 50, v34
	s_nop 0
	v_cndmask_b32_e32 v26, v176, v26, vcc
	v_cmp_le_i32_e32 vcc, v35, v152
	v_or_b32_e32 v35, 19, v34
	s_nop 0
	v_cndmask_b32_e32 v10, v176, v10, vcc
	v_cmp_le_i32_e32 vcc, v35, v152
	v_or_b32_e32 v35, 51, v34
	s_nop 0
	v_cndmask_b32_e32 v27, v176, v27, vcc
	v_cmp_le_i32_e32 vcc, v35, v152
	v_or_b32_e32 v35, 24, v34
	s_nop 0
	v_cndmask_b32_e32 v11, v176, v11, vcc
	v_cmp_le_i32_e32 vcc, v35, v152
	v_or_b32_e32 v35, 56, v34
	s_nop 0
	v_cndmask_b32_e32 v28, v176, v28, vcc
	v_cmp_le_i32_e32 vcc, v35, v152
	v_or_b32_e32 v35, 25, v34
	s_nop 0
	v_cndmask_b32_e32 v12, v176, v12, vcc
	v_cmp_le_i32_e32 vcc, v35, v152
	v_or_b32_e32 v35, 57, v34
	s_nop 0
	v_cndmask_b32_e32 v29, v176, v29, vcc
	v_cmp_le_i32_e32 vcc, v35, v152
	v_or_b32_e32 v35, 26, v34
	s_nop 0
	v_cndmask_b32_e32 v13, v176, v13, vcc
	v_cmp_le_i32_e32 vcc, v35, v152
	v_or_b32_e32 v35, 58, v34
	s_nop 0
	v_cndmask_b32_e32 v30, v176, v30, vcc
	v_cmp_le_i32_e32 vcc, v35, v152
	v_or_b32_e32 v35, 27, v34
	v_or_b32_e32 v34, 59, v34
	v_cndmask_b32_e32 v14, v176, v14, vcc
	v_cmp_le_i32_e32 vcc, v35, v152
	s_nop 1
	v_cndmask_b32_e32 v31, v176, v31, vcc
	v_cmp_le_i32_e32 vcc, v34, v152
	s_nop 1
	v_cndmask_b32_e32 v15, v176, v15, vcc

.LBB0_201:
	s_lshl_b32 s80, s2, 13
	v_or_b32_e32 v136, s80, v151
	ds_read_b64_tr_b16 v[80:81],v136 offset:0
	ds_read_b64_tr_b16 v[82:83],v136 offset:128
	ds_read_b64_tr_b16 v[84:85],v136 offset:512
	ds_read_b64_tr_b16 v[86:87],v136 offset:640
	ds_read_b64_tr_b16 v[88:89],v136 offset:4096
	ds_read_b64_tr_b16 v[90:91],v136 offset:4224
	ds_read_b64_tr_b16 v[92:93],v136 offset:4608
	ds_read_b64_tr_b16 v[94:95],v136 offset:4736
	s_waitcnt lgkmcnt(0)
	s_nop 0
	v_mfma_f32_32x32x16_bf16 v[16:31], v[64:67], v[80:83], v[16:31]
	ds_read_b64_tr_b16 v[80:81],v136 offset:2048
	ds_read_b64_tr_b16 v[82:83],v136 offset:2176
	v_mfma_f32_32x32x16_bf16 v[16:31], v[68:71], v[84:87], v[16:31]
	ds_read_b64_tr_b16 v[84:85],v136 offset:2560
	ds_read_b64_tr_b16 v[86:87],v136 offset:2688
	v_mfma_f32_32x32x16_bf16 v[16:31], v[72:75], v[88:91], v[16:31]
	ds_read_b64_tr_b16 v[88:89],v136 offset:6144
	ds_read_b64_tr_b16 v[90:91],v136 offset:6272
	v_mfma_f32_32x32x16_bf16 v[16:31], v[76:79], v[92:95], v[16:31]
	ds_read_b64_tr_b16 v[92:93],v136 offset:6656
	ds_read_b64_tr_b16 v[94:95],v136 offset:6784
	s_waitcnt lgkmcnt(0)
	v_mfma_f32_32x32x16_bf16 v[0:15], v[64:67], v[80:83], v[0:15]
	v_max_f32_e32 v64, v49, v49
	v_max_f32_e32 v65, v48, v48
	v_max_f32_e32 v64, v65, v64
	v_max3_f32 v64, v64, v50, v51
	v_max3_f32 v64, v64, v52, v53
	v_max3_f32 v64, v64, v54, v55
	v_max3_f32 v64, v64, v56, v57
	v_mfma_f32_32x32x16_bf16 v[0:15], v[68:71], v[84:87], v[0:15]
	v_max3_f32 v64, v64, v58, v59
	v_max3_f32 v64, v64, v60, v61
	v_max3_f32 v64, v64, v62, v63
	v_max3_f32 v64, v64, v32, v33
	v_max3_f32 v64, v64, v34, v35
	v_max3_f32 v64, v64, v36, v37
	v_max3_f32 v64, v64, v38, v39
	v_mfma_f32_32x32x16_bf16 v[0:15], v[72:75], v[88:91], v[0:15]
	v_max3_f32 v64, v64, v40, v41
	v_max3_f32 v64, v64, v42, v43
	v_max3_f32 v64, v64, v44, v45
	v_max3_f32 v64, v64, v46, v47
	v_mov_b32_e32 v65, v64
	s_nop 1
	v_permlane32_swap_b32_e32 v64, v65
	v_mfma_f32_32x32x16_bf16 v[0:15], v[76:79], v[92:95], v[0:15]
	v_max_f32_e32 v65, v65, v65
	v_max_f32_e32 v64, v64, v64
	v_max_f32_e32 v64, v64, v65
	v_sub_f32_e32 v65, v64, v163
	v_mul_f32_e32 v65, 0x3e000000, v65
	s_mov_b32 s10, 0x41800000
	s_lshl_b32 s87, s79, 13
	v_cmp_ge_f32_e32 vcc, s10, v65
	v_add_u32_e32 v65, s87, v162
	s_mov_b64 s[10:11], exec
	s_cmp_lg_u64 s[22:23], 0
	s_cbranch_scc0 .Lat_h1_rare
	s_waitcnt vmcnt(5)
	ds_write_b128 v65, v[120:123]
	v_add_u32_e32 v65, s87, v161
	s_waitcnt vmcnt(4)
	ds_write_b128 v65, v[124:127] offset:24576
	s_and_saveexec_b64 s[36:37], s[6:7]
	s_cbranch_execz .LBB0_203
	v_lshl_add_u32 v65, s79, 8, v164
	s_waitcnt vmcnt(3)
	ds_write_b32 v65, v165 offset:51200
	s_branch .LBB0_203
.Lat_h1_rare:
	s_waitcnt vmcnt(2)
	ds_write_b128 v65, v[120:123]
	v_add_u32_e32 v65, s87, v161
	s_waitcnt vmcnt(1)
	ds_write_b128 v65, v[124:127] offset:24576
	s_and_saveexec_b64 s[36:37], s[6:7]
	s_cbranch_execz .LBB0_203
	v_lshl_add_u32 v65, s79, 8, v164
	s_waitcnt vmcnt(0)
	ds_write_b32 v65, v165 offset:51200

.LBB0_211:
	v_add_u32_e32 v62, s3, v151
	ds_read_b64_tr_b16 v[50:51],v62 offset:0
	ds_read_b64_tr_b16 v[52:53],v62 offset:128
	ds_read_b64_tr_b16 v[54:55],v62 offset:512
	ds_read_b64_tr_b16 v[56:57],v62 offset:640
	ds_read_b64_tr_b16 v[58:59],v62 offset:4096
	ds_read_b64_tr_b16 v[60:61],v62 offset:4224
	ds_read_b64_tr_b16 v[138:139],v62 offset:4608
	ds_read_b64_tr_b16 v[140:141],v62 offset:4736
	s_waitcnt lgkmcnt(0)
	s_nop 0
	v_mfma_f32_32x32x16_bf16 v[16:31], v[32:35], v[50:53], v[16:31]
	ds_read_b64_tr_b16 v[50:51],v62 offset:2048
	ds_read_b64_tr_b16 v[52:53],v62 offset:2176
	v_mfma_f32_32x32x16_bf16 v[16:31], v[36:39], v[54:57], v[16:31]
	ds_read_b64_tr_b16 v[54:55],v62 offset:2560
	ds_read_b64_tr_b16 v[56:57],v62 offset:2688
	v_mfma_f32_32x32x16_bf16 v[16:31], v[40:43], v[58:61], v[16:31]
	ds_read_b64_tr_b16 v[58:59],v62 offset:6144
	ds_read_b64_tr_b16 v[60:61],v62 offset:6272
	v_mfma_f32_32x32x16_bf16 v[16:31], v[44:47], v[138:141], v[16:31]
	ds_read_b64_tr_b16 v[138:139],v62 offset:6656
	ds_read_b64_tr_b16 v[140:141],v62 offset:6784
	s_waitcnt lgkmcnt(0)
	v_mfma_f32_32x32x16_bf16 v[0:15], v[32:35], v[50:53], v[0:15]
	v_max_f32_e32 v32, v81, v81
	v_max_f32_e32 v33, v80, v80
	v_max_f32_e32 v32, v33, v32
	v_max3_f32 v32, v32, v82, v83
	v_max3_f32 v32, v32, v84, v85
	v_max3_f32 v32, v32, v86, v87
	v_max3_f32 v32, v32, v88, v89
	v_mfma_f32_32x32x16_bf16 v[0:15], v[36:39], v[54:57], v[0:15]
	v_max3_f32 v32, v32, v90, v91
	v_max3_f32 v32, v32, v92, v93
	v_max3_f32 v32, v32, v94, v95
	v_max3_f32 v32, v32, v64, v65
	v_max3_f32 v32, v32, v66, v67
	v_max3_f32 v32, v32, v68, v69
	v_max3_f32 v32, v32, v70, v71
	v_mfma_f32_32x32x16_bf16 v[0:15], v[40:43], v[58:61], v[0:15]
	v_max3_f32 v32, v32, v72, v73
	v_max3_f32 v32, v32, v74, v75
	v_max3_f32 v32, v32, v76, v77
	v_max3_f32 v32, v32, v78, v79
	v_mov_b32_e32 v33, v32
	s_nop 1
	v_permlane32_swap_b32_e32 v32, v33
	v_mfma_f32_32x32x16_bf16 v[0:15], v[44:47], v[138:141], v[0:15]
	v_max_f32_e32 v33, v33, v33
	v_max_f32_e32 v32, v32, v32
	v_max_f32_e32 v32, v32, v33
	v_sub_f32_e32 v33, v32, v136
	v_mul_f32_e32 v33, 0x3e000000, v33
	s_mov_b32 s3, 0x41800000
	v_cmp_ge_f32_e32 vcc, s3, v33
	s_cmp_eq_u64 vcc, exec
	s_cselect_b64 s[10:11], -1, 0
	s_andn2_b64 vcc, exec, s[22:23]
	s_cbranch_vccnz .LBB0_215
	s_cmp_ge_i32 s36, s77
	s_cbranch_scc1 .Lat_h2_rare
	v_add_u32_e32 v33, s80, v162
	s_waitcnt vmcnt(5)
	ds_write_b128 v33, v[112:115]
	v_add_u32_e32 v33, s80, v161
	s_waitcnt vmcnt(4)
	ds_write_b128 v33, v[116:119] offset:24576
	s_and_saveexec_b64 s[22:23], s[6:7]
	s_cbranch_execz .LBB0_214
	v_lshl_add_u32 v33, s2, 8, v164
	s_waitcnt vmcnt(3)
	ds_write_b32 v33, v160 offset:51200
	s_branch .LBB0_214
.Lat_h2_rare:
	v_add_u32_e32 v33, s80, v162
	s_waitcnt vmcnt(2)
	ds_write_b128 v33, v[112:115]
	v_add_u32_e32 v33, s80, v161
	s_waitcnt vmcnt(1)
	ds_write_b128 v33, v[116:119] offset:24576
	s_and_saveexec_b64 s[22:23], s[6:7]
	s_cbranch_execz .LBB0_214
	v_lshl_add_u32 v33, s2, 8, v164
	s_waitcnt vmcnt(0)
	ds_write_b32 v33, v160 offset:51200
